# fused block pipelined + removed forced vmcnt(0) between independent K and V tile loads in attention
# speedup vs baseline: 1.0241x; 1.0151x over previous
; #define ATT_LOADK(t) do { const bf16_t* kp_ = kbase + (size_t)(64 * (t)) * 768 + kgo; _Pragma("unroll") for (int i = 0; i < 3; ++i) kreg[i] = *(const u32x4*)(kp_ + 64 * i); } while (0)
; #define ATT_LOADV(t) do { const bf16_t* vp_ = vbase + 64 * (t) + vgo; _Pragma("unroll") for (int i = 0; i < 2; ++i) vreg[i] = *(const u32x4*)(vp_ + 32 * i); } while (0)
; DI void attn_unit(LAS unsigned char* lds, const bf16_t* __restrict__ Q, const bf16_t* __restrict__ Kg, const bf16_t* __restrict__ VT, bf16_t* __restrict__ MIX, int b, int h, int c0, int nq, int desc) {
;     ...
;     if (t + 2 < nt) ATT_LOADK(TAU(t + 2));
;     if (t + 1 < nt) ATT_LOADV(taun);
.LBB0_541:
	s_add_i32 s12, s23, 0x102
	s_cmp_lt_i32 s12, s17
	s_cselect_b64 s[28:29], -1, 0
	s_cmp_ge_i32 s12, s17
	s_cbranch_scc1 .LBB0_543
	s_sub_i32 s12, s68, 64
	v_lshl_add_u64 v[98:99], s[12:13], 1, v[202:203]
	global_load_dwordx4 v[190:193], v[98:99], off
	global_load_dwordx4 v[194:197], v[98:99], off offset:64

; #define ATT_LOADK(t) do { const bf16_t* kp_ = kbase + (size_t)(64 * (t)) * 768 + kgo; _Pragma("unroll") for (int i = 0; i < 3; ++i) kreg[i] = *(const u32x4*)(kp_ + 64 * i); } while (0)
; #define ATT_LOADV(t) do { const bf16_t* vp_ = vbase + 64 * (t) + vgo; _Pragma("unroll") for (int i = 0; i < 2; ++i) vreg[i] = *(const u32x4*)(vp_ + 32 * i); } while (0)
; DI void attn_unit(LAS unsigned char* lds, const bf16_t* __restrict__ Q, const bf16_t* __restrict__ Kg, const bf16_t* __restrict__ VT, bf16_t* __restrict__ MIX, int b, int h, int c0, int nq, int desc) {
;     ...
;     if (t + 2 < nt) ATT_LOADK(TAU(t + 2));
;     if (t + 1 < nt) ATT_LOADV(taun);
.LBB0_571:
	s_add_i32 s23, s70, -1
	s_cmp_lt_i32 s23, s17
	s_cselect_b64 s[28:29], -1, 0
	s_cmp_ge_i32 s23, s17
	s_cbranch_scc1 .LBB0_573
	s_add_i32 s6, s69, 64
	s_ashr_i32 s7, s6, 31
	v_lshl_add_u64 v[2:3], s[6:7], 1, v[220:221]
	global_load_dwordx4 v[160:163], v[2:3], off
	global_load_dwordx4 v[164:167], v[2:3], off offset:64

; #define ATT_LOADK(t) do { const bf16_t* kp_ = kbase + (size_t)(64 * (t)) * 768 + kgo; _Pragma("unroll") for (int i = 0; i < 3; ++i) kreg[i] = *(const u32x4*)(kp_ + 64 * i); } while (0)
; #define ATT_LOADV(t) do { const bf16_t* vp_ = vbase + 64 * (t) + vgo; _Pragma("unroll") for (int i = 0; i < 2; ++i) vreg[i] = *(const u32x4*)(vp_ + 32 * i); } while (0)
; DI void attn_unit(LAS unsigned char* lds, const bf16_t* __restrict__ Q, const bf16_t* __restrict__ Kg, const bf16_t* __restrict__ VT, bf16_t* __restrict__ MIX, int b, int h, int c0, int nq, int desc) {
;     ...
;     if (t + 2 < nt) ATT_LOADK(TAU(t + 2));
;     if (t + 1 < nt) ATT_LOADV(taun);
.LBB0_598:
	s_not_b32 s6, s23
	s_add_i32 s6, s12, s6
	s_cmp_gt_i32 s12, s23
	s_cselect_b64 s[28:29], -1, 0
	s_cmp_le_i32 s12, s23
	s_cbranch_scc1 .LBB0_600
	s_lshl_b32 s16, s6, 6
	s_ashr_i32 s17, s16, 31
	v_lshl_add_u64 v[2:3], s[16:17], 1, v[220:221]
	global_load_dwordx4 v[160:163], v[2:3], off
	global_load_dwordx4 v[164:167], v[2:3], off offset:64

; #define ATT_LOADK(t) do { const bf16_t* kp_ = kbase + (size_t)(64 * (t)) * 768 + kgo; _Pragma("unroll") for (int i = 0; i < 3; ++i) kreg[i] = *(const u32x4*)(kp_ + 64 * i); } while (0)
; #define ATT_LOADV(t) do { const bf16_t* vp_ = vbase + 64 * (t) + vgo; _Pragma("unroll") for (int i = 0; i < 2; ++i) vreg[i] = *(const u32x4*)(vp_ + 32 * i); } while (0)
; DI void attn_unit(LAS unsigned char* lds, const bf16_t* __restrict__ Q, const bf16_t* __restrict__ Kg, const bf16_t* __restrict__ VT, bf16_t* __restrict__ MIX, int b, int h, int c0, int nq, int desc) {
;     ...
;     if (t + 2 < nt) ATT_LOADK(TAU(t + 2));
;     if (t + 1 < nt) ATT_LOADV(taun);
.LBB0_2552:
	s_add_i32 s0, s23, 0x102
	s_cmp_lt_i32 s0, s17
	s_cselect_b64 s[28:29], -1, 0
	s_cmp_ge_i32 s0, s17
	s_cbranch_scc1 .LBB0_2554
	s_sub_i32 s12, s68, 64
	v_lshl_add_u64 v[98:99], s[12:13], 1, v[202:203]
	global_load_dwordx4 v[190:193], v[98:99], off
	global_load_dwordx4 v[194:197], v[98:99], off offset:64

; #define ATT_LOADK(t) do { const bf16_t* kp_ = kbase + (size_t)(64 * (t)) * 768 + kgo; _Pragma("unroll") for (int i = 0; i < 3; ++i) kreg[i] = *(const u32x4*)(kp_ + 64 * i); } while (0)
; #define ATT_LOADV(t) do { const bf16_t* vp_ = vbase + 64 * (t) + vgo; _Pragma("unroll") for (int i = 0; i < 2; ++i) vreg[i] = *(const u32x4*)(vp_ + 32 * i); } while (0)
; DI void attn_unit(LAS unsigned char* lds, const bf16_t* __restrict__ Q, const bf16_t* __restrict__ Kg, const bf16_t* __restrict__ VT, bf16_t* __restrict__ MIX, int b, int h, int c0, int nq, int desc) {
;     ...
;     if (t + 2 < nt) ATT_LOADK(TAU(t + 2));
;     if (t + 1 < nt) ATT_LOADV(taun);
.LBB0_2609:
	s_not_b32 s0, s23
	s_add_i32 s6, s12, s0
	s_cmp_gt_i32 s12, s23
	s_cselect_b64 s[28:29], -1, 0
	s_cmp_le_i32 s12, s23
	s_cbranch_scc1 .LBB0_2611
	s_lshl_b32 s16, s6, 6
	s_ashr_i32 s17, s16, 31
	v_lshl_add_u64 v[2:3], s[16:17], 1, v[220:221]
	global_load_dwordx4 v[160:163], v[2:3], off
	global_load_dwordx4 v[164:167], v[2:3], off offset:64
